# cooperative-groups grid sync replaced by a hand-written XCD-hierarchical barrier instance on the same barrier words
# speedup vs baseline: 1.0249x; 1.0055x over previous
.LBB0_508:
	s_waitcnt vmcnt(0) lgkmcnt(0)
	s_barrier
	v_cmp_eq_u32_e32 vcc, 0, v164
	s_and_saveexec_b64 s[0:1], vcc
	v_readlane_b32 s76, v255, 11
	v_readlane_b32 s77, v255, 12
	s_cbranch_execz .Lxg_done
	v_mov_b32_e32 v1, 0x20400
	ds_read2_b32 v[2:3], v1 offset1:1
	s_add_u32 s8, s86, 0x1400
	s_addc_u32 s9, s87, 0
	s_add_u32 s10, s86, 0x2400
	s_addc_u32 s11, s87, 0
	s_add_u32 s4, s86, 0x3400
	s_addc_u32 s5, s87, 0
	s_lshl_b32 s6, s33, 8
	v_mov_b32_e32 v0, s6
	v_mov_b32_e32 v1, 1
	global_atomic_add v1, v0, v1, s[8:9] sc0
	s_waitcnt vmcnt(0) lgkmcnt(0)
	v_lshlrev_b32_e32 v2, 2, v2
	v_add_u32_e32 v1, 1, v1
	v_cmp_eq_u32_e32 vcc, v1, v2
	s_cbranch_vccz .Lxg_follower
	buffer_wbl2 sc1
	s_waitcnt vmcnt(0)
	v_mov_b32_e32 v1, 1
	v_mov_b32_e32 v0, 0
	global_atomic_add v1, v0, v1, s[4:5] sc0
	s_waitcnt vmcnt(0)
	v_lshlrev_b32_e32 v3, 2, v3
	v_add_u32_e32 v1, 1, v1
	v_cmp_eq_u32_e32 vcc, v1, v3
	s_cbranch_vccz .Lxg_topwait
	v_mov_b32_e32 v1, 1
	global_atomic_add v0, v1, s[4:5] offset:256
	s_branch .Lxg_toprel
.Lxg_topwait:
	s_mov_b32 s7, 0
.Lxg_tw:
	s_sleep 1
	global_load_dword v1, v0, s[4:5] offset:256 sc1
	s_waitcnt vmcnt(0)
	v_cmp_ne_u32_e32 vcc, 3, v1
	s_cbranch_vccnz .Lxg_toprel
	s_add_u32 s7, s7, 1
	s_cmp_lt_u32 s7, 0x100000
	s_cbranch_scc1 .Lxg_tw
.Lxg_toprel:
	s_waitcnt vmcnt(0)
	buffer_inv sc1
	v_mov_b32_e32 v0, s6
	v_mov_b32_e32 v1, 1
	global_atomic_add v0, v1, s[10:11]
	s_waitcnt vmcnt(0)
	s_branch .Lxg_done
.Lxg_follower:
	v_mov_b32_e32 v0, s6
	s_mov_b32 s7, 0
.Lxg_fw:
	s_sleep 1
	global_load_dword v1, v0, s[10:11] sc1
	s_waitcnt vmcnt(0)
	v_cmp_ne_u32_e32 vcc, 3, v1
	s_cbranch_vccnz .Lxg_frel
	s_add_u32 s7, s7, 1
	s_cmp_lt_u32 s7, 0x100000
	s_cbranch_scc1 .Lxg_fw
.Lxg_frel:
	s_waitcnt vmcnt(0)
	buffer_inv sc1
	s_waitcnt vmcnt(0)
.Lxg_done:
.LBB0_518:
	s_or_b64 exec, exec, s[0:1]
	v_and_b32_e32 v0, 0x78, v221
	s_movk_i32 s0, 0x4000
	v_mov_b32_e32 v9, 0
	v_cmp_gt_i32_e64 s[6:7], s0, v178
	v_ashrrev_i32_e32 v179, 31, v178
	v_lshlrev_b32_e32 v227, 2, v0
	s_barrier
	s_and_saveexec_b64 s[20:21], s[6:7]
	s_cbranch_execz .LBB0_521
	v_readlane_b32 s44, v255, 13
	v_readlane_b32 s45, v255, 14
	s_nop 4
	global_load_dwordx4 v[0:3], v227, s[44:45]
	global_load_dwordx4 v[4:7], v227, s[44:45] offset:16
	s_lshl_b32 s22, s30, 3
	v_readlane_b32 s46, v255, 15
	s_movk_i32 s0, 0x1200
	v_mov_b64_e32 v[10:11], s[28:29]
	s_ashr_i32 s23, s22, 31
	v_lshlrev_b64 v[14:15], 11, v[178:179]
	v_lshlrev_b32_e32 v8, 4, v210
	v_mad_i64_i32 v[10:11], s[0:1], v178, s0, v[10:11]
	s_mul_i32 s34, s30, 0x9000
	s_mul_hi_i32 s35, s22, 0x1200
	v_lshl_add_u64 v[12:13], s[26:27], 0, v[14:15]
	s_lshl_b64 s[40:41], s[22:23], 11
	v_lshl_add_u64 v[14:15], s[28:29], 0, v[14:15]
	s_mov_b64 s[44:45], 0
	v_mov_b32_e32 v20, 0x358637bd
	s_mov_b32 s23, 0x800000
	s_movk_i32 s46, 0x3fff
	v_mov_b32_e32 v21, v178
	v_readlane_b32 s47, v255, 16
	v_readlane_b32 s48, v255, 17
	v_readlane_b32 s49, v255, 18
	v_readlane_b32 s50, v255, 19
	v_readlane_b32 s51, v255, 20
	v_readlane_b32 s52, v255, 21
	v_readlane_b32 s53, v255, 22
	v_readlane_b32 s54, v255, 23
	v_readlane_b32 s55, v255, 24
	v_readlane_b32 s56, v255, 25
	v_readlane_b32 s57, v255, 26
	v_readlane_b32 s58, v255, 27
	v_readlane_b32 s59, v255, 28
